# baseline (speedup 1.0000x reference)
; __device__ __forceinline__ float silu_(float x) { return x * rcp_(1.f + __expf(-x)); }
; template <int EPI>
; __device__ __forceinline__ void gemm_phase(const Params& p, const u16* __restrict__ A, const u16* __restrict__ Bt, int K, int nN,
;                            u16* __restrict__ Cout, int ldc) {
;     ...
; #pragma unroll
;       for (int m = 0; m < 8; ++m) {
; #pragma unroll
;         for (int j = 0; j < 4; ++j) {
;           const float rs = rsl[wr * 128 + m * 16 + fqe * 4 + j];
;           u16* d = stg + (wr * 128 + m * 16 + fqe * 4 + j) * 128 + (fre & 7);
; #pragma unroll
;           for (int n2 = 0; n2 < 2; ++n2) {
;             const float g = acc[m][2 * n2][j] * rs, u = acc[m][2 * n2 + 1][j] * rs;
;             const int chunk = (wc * 4 + n2 * 2 + (fre >> 3)) ^ fqe;
;             d[chunk * 8] = f2bf(silu_(g) * u);
;           }
;         }
;         __builtin_amdgcn_sched_barrier(0);
;       }
.LBB0_1126:
	v_lshl_add_u32 v222, v192, 2, v196
	v_lshl_add_u32 v223, v222, 2, v187
	ds_read_b128 v[128:131], v223 offset:0
	ds_read_b128 v[132:135], v223 offset:64
	ds_read_b128 v[136:139], v223 offset:128
	ds_read_b128 v[140:143], v223 offset:192
	ds_read_b128 v[144:147], v223 offset:256
	ds_read_b128 v[148:151], v223 offset:320
	ds_read_b128 v[152:155], v223 offset:384
	ds_read_b128 v[156:159], v223 offset:448
	v_and_b32_e32 v224, 7, v174
	v_lshrrev_b32_e32 v225, 3, v174
	v_add_u32_e32 v225, v225, v197
	v_lshlrev_b32_e32 v224, 1, v224
	v_lshl_or_b32 v224, v222, 8, v224
	v_xor_b32_e32 v226, v225, v192
	v_add_u32_e32 v227, 2, v225
	v_xor_b32_e32 v227, v227, v192
	v_lshl_add_u32 v160, v226, 4, v224
	v_lshl_add_u32 v161, v227, 4, v224
	v_add_u32_e32 v160, 0x10000, v160
	v_add_u32_e32 v161, 0x10000, v161
	s_waitcnt lgkmcnt(0)
	v_mul_f32_e32 v162, v124, v128
	v_mul_f32_e32 v163, v125, v129
	v_mul_f32_e32 v164, v126, v130
	v_mul_f32_e32 v165, v127, v131
	v_mul_f32_e32 v166, v116, v128
	v_mul_f32_e32 v167, v117, v129
	v_mul_f32_e32 v168, v118, v130
	v_mul_f32_e32 v169, v119, v131
	v_mul_f32_e32 v214, 0xbfb8aa3b, v162
	v_mul_f32_e32 v215, 0xbfb8aa3b, v163
	v_mul_f32_e32 v216, 0xbfb8aa3b, v164
	v_mul_f32_e32 v217, 0xbfb8aa3b, v165
	v_mul_f32_e32 v218, 0xbfb8aa3b, v166
	v_mul_f32_e32 v219, 0xbfb8aa3b, v167
	v_mul_f32_e32 v220, 0xbfb8aa3b, v168
	v_mul_f32_e32 v221, 0xbfb8aa3b, v169
	v_exp_f32_e32 v214, v214
	v_exp_f32_e32 v215, v215
	v_exp_f32_e32 v216, v216
	v_exp_f32_e32 v217, v217
	v_exp_f32_e32 v218, v218
	v_exp_f32_e32 v219, v219
	v_exp_f32_e32 v220, v220
	v_exp_f32_e32 v221, v221
	v_mul_f32_e32 v206, v120, v128
	v_mul_f32_e32 v207, v121, v129
	v_mul_f32_e32 v208, v122, v130
	v_mul_f32_e32 v209, v123, v131
	v_mul_f32_e32 v210, v112, v128
	v_mul_f32_e32 v211, v113, v129
	v_mul_f32_e32 v212, v114, v130
	v_mul_f32_e32 v213, v115, v131
	v_add_f32_e32 v214, 1.0, v214
	v_add_f32_e32 v215, 1.0, v215
	v_add_f32_e32 v216, 1.0, v216
	v_add_f32_e32 v217, 1.0, v217
	v_add_f32_e32 v218, 1.0, v218
	v_add_f32_e32 v219, 1.0, v219
	v_add_f32_e32 v220, 1.0, v220
	v_add_f32_e32 v221, 1.0, v221
	v_rcp_f32_e32 v214, v214
	v_rcp_f32_e32 v215, v215
	v_rcp_f32_e32 v216, v216
	v_rcp_f32_e32 v217, v217
	v_rcp_f32_e32 v218, v218
	v_rcp_f32_e32 v219, v219
	v_rcp_f32_e32 v220, v220
	v_rcp_f32_e32 v221, v221
	v_mul_f32_e32 v162, v162, v214
	v_mul_f32_e32 v163, v163, v215
	v_mul_f32_e32 v164, v164, v216
	v_mul_f32_e32 v165, v165, v217
	v_mul_f32_e32 v166, v166, v218
	v_mul_f32_e32 v167, v167, v219
	v_mul_f32_e32 v168, v168, v220
	v_mul_f32_e32 v169, v169, v221
	v_mul_f32_e32 v206, v206, v162
	v_mul_f32_e32 v207, v207, v163
	v_mul_f32_e32 v208, v208, v164
	v_mul_f32_e32 v209, v209, v165
	v_mul_f32_e32 v210, v210, v166
	v_mul_f32_e32 v211, v211, v167
	v_mul_f32_e32 v212, v212, v168
	v_mul_f32_e32 v213, v213, v169
	v_cvt_pk_bf16_f32 v206, v206, s0
	v_cvt_pk_bf16_f32 v207, v207, s0
	v_cvt_pk_bf16_f32 v208, v208, s0
	v_cvt_pk_bf16_f32 v209, v209, s0
	v_cvt_pk_bf16_f32 v210, v210, s0
	v_cvt_pk_bf16_f32 v211, v211, s0
	v_cvt_pk_bf16_f32 v212, v212, s0
	v_cvt_pk_bf16_f32 v213, v213, s0
	ds_write_b16 v160, v206 offset:0
	ds_write_b16 v160, v207 offset:256
	ds_write_b16 v160, v208 offset:512
	ds_write_b16 v160, v209 offset:768
	ds_write_b16 v161, v210 offset:0
	ds_write_b16 v161, v211 offset:256
	ds_write_b16 v161, v212 offset:512
	ds_write_b16 v161, v213 offset:768
	v_mul_f32_e32 v162, v108, v132
	v_mul_f32_e32 v163, v109, v133
	v_mul_f32_e32 v164, v110, v134
	v_mul_f32_e32 v165, v111, v135
	v_mul_f32_e32 v166, v100, v132
	v_mul_f32_e32 v167, v101, v133
	v_mul_f32_e32 v168, v102, v134
	v_mul_f32_e32 v169, v103, v135
	v_mul_f32_e32 v214, 0xbfb8aa3b, v162
	v_mul_f32_e32 v215, 0xbfb8aa3b, v163
	v_mul_f32_e32 v216, 0xbfb8aa3b, v164
	v_mul_f32_e32 v217, 0xbfb8aa3b, v165
	v_mul_f32_e32 v218, 0xbfb8aa3b, v166
	v_mul_f32_e32 v219, 0xbfb8aa3b, v167
	v_mul_f32_e32 v220, 0xbfb8aa3b, v168
	v_mul_f32_e32 v221, 0xbfb8aa3b, v169
	v_exp_f32_e32 v214, v214
	v_exp_f32_e32 v215, v215
	v_exp_f32_e32 v216, v216
	v_exp_f32_e32 v217, v217
	v_exp_f32_e32 v218, v218
	v_exp_f32_e32 v219, v219
	v_exp_f32_e32 v220, v220
	v_exp_f32_e32 v221, v221
	v_mul_f32_e32 v206, v104, v132
	v_mul_f32_e32 v207, v105, v133
	v_mul_f32_e32 v208, v106, v134
	v_mul_f32_e32 v209, v107, v135
	v_mul_f32_e32 v210, v96, v132
	v_mul_f32_e32 v211, v97, v133
	v_mul_f32_e32 v212, v98, v134
	v_mul_f32_e32 v213, v99, v135
	v_add_f32_e32 v214, 1.0, v214
	v_add_f32_e32 v215, 1.0, v215
	v_add_f32_e32 v216, 1.0, v216
	v_add_f32_e32 v217, 1.0, v217
	v_add_f32_e32 v218, 1.0, v218
	v_add_f32_e32 v219, 1.0, v219
	v_add_f32_e32 v220, 1.0, v220
	v_add_f32_e32 v221, 1.0, v221
	v_rcp_f32_e32 v214, v214
	v_rcp_f32_e32 v215, v215
	v_rcp_f32_e32 v216, v216
	v_rcp_f32_e32 v217, v217
	v_rcp_f32_e32 v218, v218
	v_rcp_f32_e32 v219, v219
	v_rcp_f32_e32 v220, v220
	v_rcp_f32_e32 v221, v221
	v_mul_f32_e32 v162, v162, v214
	v_mul_f32_e32 v163, v163, v215
	v_mul_f32_e32 v164, v164, v216
	v_mul_f32_e32 v165, v165, v217
	v_mul_f32_e32 v166, v166, v218
	v_mul_f32_e32 v167, v167, v219
	v_mul_f32_e32 v168, v168, v220
	v_mul_f32_e32 v169, v169, v221
	v_mul_f32_e32 v206, v206, v162
	v_mul_f32_e32 v207, v207, v163
	v_mul_f32_e32 v208, v208, v164
	v_mul_f32_e32 v209, v209, v165
	v_mul_f32_e32 v210, v210, v166
	v_mul_f32_e32 v211, v211, v167
	v_mul_f32_e32 v212, v212, v168
	v_mul_f32_e32 v213, v213, v169
	v_cvt_pk_bf16_f32 v206, v206, s0
	v_cvt_pk_bf16_f32 v207, v207, s0
	v_cvt_pk_bf16_f32 v208, v208, s0
	v_cvt_pk_bf16_f32 v209, v209, s0
	v_cvt_pk_bf16_f32 v210, v210, s0
	v_cvt_pk_bf16_f32 v211, v211, s0
	v_cvt_pk_bf16_f32 v212, v212, s0
	v_cvt_pk_bf16_f32 v213, v213, s0
; __device__ __forceinline__ float silu_(float x) { return x * rcp_(1.f + __expf(-x)); }
; template <int EPI>
; __device__ __forceinline__ void gemm_phase(const Params& p, const u16* __restrict__ A, const u16* __restrict__ Bt, int K, int nN,
;                            u16* __restrict__ Cout, int ldc) {
;     ...
; #pragma unroll
;       for (int m = 0; m < 8; ++m) {
; #pragma unroll
;         for (int j = 0; j < 4; ++j) {
;           const float rs = rsl[wr * 128 + m * 16 + fqe * 4 + j];
;           u16* d = stg + (wr * 128 + m * 16 + fqe * 4 + j) * 128 + (fre & 7);
; #pragma unroll
;           for (int n2 = 0; n2 < 2; ++n2) {
;             const float g = acc[m][2 * n2][j] * rs, u = acc[m][2 * n2 + 1][j] * rs;
;             const int chunk = (wc * 4 + n2 * 2 + (fre >> 3)) ^ fqe;
;             d[chunk * 8] = f2bf(silu_(g) * u);
;           }
;         }
;         __builtin_amdgcn_sched_barrier(0);
;       }
	ds_write_b16 v160, v206 offset:4096
	ds_write_b16 v160, v207 offset:4352
	ds_write_b16 v160, v208 offset:4608
	ds_write_b16 v160, v209 offset:4864
	ds_write_b16 v161, v210 offset:4096
	ds_write_b16 v161, v211 offset:4352
	ds_write_b16 v161, v212 offset:4608
	ds_write_b16 v161, v213 offset:4864
	v_mul_f32_e32 v162, v92, v136
	v_mul_f32_e32 v163, v93, v137
	v_mul_f32_e32 v164, v94, v138
	v_mul_f32_e32 v165, v95, v139
	v_mul_f32_e32 v166, v84, v136
	v_mul_f32_e32 v167, v85, v137
	v_mul_f32_e32 v168, v86, v138
	v_mul_f32_e32 v169, v87, v139
	v_mul_f32_e32 v214, 0xbfb8aa3b, v162
	v_mul_f32_e32 v215, 0xbfb8aa3b, v163
	v_mul_f32_e32 v216, 0xbfb8aa3b, v164
	v_mul_f32_e32 v217, 0xbfb8aa3b, v165
	v_mul_f32_e32 v218, 0xbfb8aa3b, v166
	v_mul_f32_e32 v219, 0xbfb8aa3b, v167
	v_mul_f32_e32 v220, 0xbfb8aa3b, v168
	v_mul_f32_e32 v221, 0xbfb8aa3b, v169
	v_exp_f32_e32 v214, v214
	v_exp_f32_e32 v215, v215
	v_exp_f32_e32 v216, v216
	v_exp_f32_e32 v217, v217
	v_exp_f32_e32 v218, v218
	v_exp_f32_e32 v219, v219
	v_exp_f32_e32 v220, v220
	v_exp_f32_e32 v221, v221
	v_mul_f32_e32 v206, v88, v136
	v_mul_f32_e32 v207, v89, v137
	v_mul_f32_e32 v208, v90, v138
	v_mul_f32_e32 v209, v91, v139
	v_mul_f32_e32 v210, v80, v136
	v_mul_f32_e32 v211, v81, v137
	v_mul_f32_e32 v212, v82, v138
	v_mul_f32_e32 v213, v83, v139
	v_add_f32_e32 v214, 1.0, v214
	v_add_f32_e32 v215, 1.0, v215
	v_add_f32_e32 v216, 1.0, v216
	v_add_f32_e32 v217, 1.0, v217
	v_add_f32_e32 v218, 1.0, v218
	v_add_f32_e32 v219, 1.0, v219
	v_add_f32_e32 v220, 1.0, v220
	v_add_f32_e32 v221, 1.0, v221
	v_rcp_f32_e32 v214, v214
	v_rcp_f32_e32 v215, v215
	v_rcp_f32_e32 v216, v216
	v_rcp_f32_e32 v217, v217
	v_rcp_f32_e32 v218, v218
	v_rcp_f32_e32 v219, v219
	v_rcp_f32_e32 v220, v220
	v_rcp_f32_e32 v221, v221
	v_mul_f32_e32 v162, v162, v214
	v_mul_f32_e32 v163, v163, v215
	v_mul_f32_e32 v164, v164, v216
	v_mul_f32_e32 v165, v165, v217
	v_mul_f32_e32 v166, v166, v218
	v_mul_f32_e32 v167, v167, v219
	v_mul_f32_e32 v168, v168, v220
	v_mul_f32_e32 v169, v169, v221
	v_mul_f32_e32 v206, v206, v162
	v_mul_f32_e32 v207, v207, v163
	v_mul_f32_e32 v208, v208, v164
	v_mul_f32_e32 v209, v209, v165
	v_mul_f32_e32 v210, v210, v166
	v_mul_f32_e32 v211, v211, v167
	v_mul_f32_e32 v212, v212, v168
	v_mul_f32_e32 v213, v213, v169
	v_cvt_pk_bf16_f32 v206, v206, s0
	v_cvt_pk_bf16_f32 v207, v207, s0
	v_cvt_pk_bf16_f32 v208, v208, s0
	v_cvt_pk_bf16_f32 v209, v209, s0
	v_cvt_pk_bf16_f32 v210, v210, s0
	v_cvt_pk_bf16_f32 v211, v211, s0
	v_cvt_pk_bf16_f32 v212, v212, s0
	v_cvt_pk_bf16_f32 v213, v213, s0
	ds_write_b16 v160, v206 offset:8192
	ds_write_b16 v160, v207 offset:8448
	ds_write_b16 v160, v208 offset:8704
	ds_write_b16 v160, v209 offset:8960
	ds_write_b16 v161, v210 offset:8192
	ds_write_b16 v161, v211 offset:8448
	ds_write_b16 v161, v212 offset:8704
	ds_write_b16 v161, v213 offset:8960
	v_mul_f32_e32 v162, v76, v140
	v_mul_f32_e32 v163, v77, v141
	v_mul_f32_e32 v164, v78, v142
	v_mul_f32_e32 v165, v79, v143
	v_mul_f32_e32 v166, v68, v140
	v_mul_f32_e32 v167, v69, v141
	v_mul_f32_e32 v168, v70, v142
	v_mul_f32_e32 v169, v71, v143
	v_mul_f32_e32 v214, 0xbfb8aa3b, v162
	v_mul_f32_e32 v215, 0xbfb8aa3b, v163
	v_mul_f32_e32 v216, 0xbfb8aa3b, v164
	v_mul_f32_e32 v217, 0xbfb8aa3b, v165
	v_mul_f32_e32 v218, 0xbfb8aa3b, v166
	v_mul_f32_e32 v219, 0xbfb8aa3b, v167
	v_mul_f32_e32 v220, 0xbfb8aa3b, v168
	v_mul_f32_e32 v221, 0xbfb8aa3b, v169
	v_exp_f32_e32 v214, v214
	v_exp_f32_e32 v215, v215
	v_exp_f32_e32 v216, v216
	v_exp_f32_e32 v217, v217
	v_exp_f32_e32 v218, v218
	v_exp_f32_e32 v219, v219
	v_exp_f32_e32 v220, v220
	v_exp_f32_e32 v221, v221
	v_mul_f32_e32 v206, v72, v140
	v_mul_f32_e32 v207, v73, v141
	v_mul_f32_e32 v208, v74, v142
	v_mul_f32_e32 v209, v75, v143
	v_mul_f32_e32 v210, v64, v140
	v_mul_f32_e32 v211, v65, v141
	v_mul_f32_e32 v212, v66, v142
	v_mul_f32_e32 v213, v67, v143
	v_add_f32_e32 v214, 1.0, v214
	v_add_f32_e32 v215, 1.0, v215
	v_add_f32_e32 v216, 1.0, v216
	v_add_f32_e32 v217, 1.0, v217
	v_add_f32_e32 v218, 1.0, v218
	v_add_f32_e32 v219, 1.0, v219
	v_add_f32_e32 v220, 1.0, v220
	v_add_f32_e32 v221, 1.0, v221
	v_rcp_f32_e32 v214, v214
	v_rcp_f32_e32 v215, v215
	v_rcp_f32_e32 v216, v216
	v_rcp_f32_e32 v217, v217
	v_rcp_f32_e32 v218, v218
	v_rcp_f32_e32 v219, v219
	v_rcp_f32_e32 v220, v220
	v_rcp_f32_e32 v221, v221
	v_mul_f32_e32 v162, v162, v214
	v_mul_f32_e32 v163, v163, v215
	v_mul_f32_e32 v164, v164, v216
	v_mul_f32_e32 v165, v165, v217
	v_mul_f32_e32 v166, v166, v218
	v_mul_f32_e32 v167, v167, v219
	v_mul_f32_e32 v168, v168, v220
	v_mul_f32_e32 v169, v169, v221
	v_mul_f32_e32 v206, v206, v162
	v_mul_f32_e32 v207, v207, v163
	v_mul_f32_e32 v208, v208, v164
	v_mul_f32_e32 v209, v209, v165
	v_mul_f32_e32 v210, v210, v166
	v_mul_f32_e32 v211, v211, v167
	v_mul_f32_e32 v212, v212, v168
	v_mul_f32_e32 v213, v213, v169
	v_cvt_pk_bf16_f32 v206, v206, s0
	v_cvt_pk_bf16_f32 v207, v207, s0
	v_cvt_pk_bf16_f32 v208, v208, s0
	v_cvt_pk_bf16_f32 v209, v209, s0
	v_cvt_pk_bf16_f32 v210, v210, s0
	v_cvt_pk_bf16_f32 v211, v211, s0
	v_cvt_pk_bf16_f32 v212, v212, s0
	v_cvt_pk_bf16_f32 v213, v213, s0
	ds_write_b16 v160, v206 offset:12288
	ds_write_b16 v160, v207 offset:12544
	ds_write_b16 v160, v208 offset:12800
	ds_write_b16 v160, v209 offset:13056
	ds_write_b16 v161, v210 offset:12288
	ds_write_b16 v161, v211 offset:12544
	ds_write_b16 v161, v212 offset:12800
	ds_write_b16 v161, v213 offset:13056
	v_mul_f32_e32 v162, v60, v144
	v_mul_f32_e32 v163, v61, v145
	v_mul_f32_e32 v164, v62, v146
	v_mul_f32_e32 v165, v63, v147
	v_mul_f32_e32 v166, v52, v144
	v_mul_f32_e32 v167, v53, v145
	v_mul_f32_e32 v168, v54, v146
	v_mul_f32_e32 v169, v55, v147
; __device__ __forceinline__ float silu_(float x) { return x * rcp_(1.f + __expf(-x)); }
; template <int EPI>
; __device__ __forceinline__ void gemm_phase(const Params& p, const u16* __restrict__ A, const u16* __restrict__ Bt, int K, int nN,
;                            u16* __restrict__ Cout, int ldc) {
;     ...
; #pragma unroll
;       for (int m = 0; m < 8; ++m) {
; #pragma unroll
;         for (int j = 0; j < 4; ++j) {
;           const float rs = rsl[wr * 128 + m * 16 + fqe * 4 + j];
;           u16* d = stg + (wr * 128 + m * 16 + fqe * 4 + j) * 128 + (fre & 7);
; #pragma unroll
;           for (int n2 = 0; n2 < 2; ++n2) {
;             const float g = acc[m][2 * n2][j] * rs, u = acc[m][2 * n2 + 1][j] * rs;
;             const int chunk = (wc * 4 + n2 * 2 + (fre >> 3)) ^ fqe;
;             d[chunk * 8] = f2bf(silu_(g) * u);
;           }
;         }
;         __builtin_amdgcn_sched_barrier(0);
;       }
	v_mul_f32_e32 v214, 0xbfb8aa3b, v162
	v_mul_f32_e32 v215, 0xbfb8aa3b, v163
	v_mul_f32_e32 v216, 0xbfb8aa3b, v164
	v_mul_f32_e32 v217, 0xbfb8aa3b, v165
	v_mul_f32_e32 v218, 0xbfb8aa3b, v166
	v_mul_f32_e32 v219, 0xbfb8aa3b, v167
	v_mul_f32_e32 v220, 0xbfb8aa3b, v168
	v_mul_f32_e32 v221, 0xbfb8aa3b, v169
	v_exp_f32_e32 v214, v214
	v_exp_f32_e32 v215, v215
	v_exp_f32_e32 v216, v216
	v_exp_f32_e32 v217, v217
	v_exp_f32_e32 v218, v218
	v_exp_f32_e32 v219, v219
	v_exp_f32_e32 v220, v220
	v_exp_f32_e32 v221, v221
	v_mul_f32_e32 v206, v56, v144
	v_mul_f32_e32 v207, v57, v145
	v_mul_f32_e32 v208, v58, v146
	v_mul_f32_e32 v209, v59, v147
	v_mul_f32_e32 v210, v48, v144
	v_mul_f32_e32 v211, v49, v145
	v_mul_f32_e32 v212, v50, v146
	v_mul_f32_e32 v213, v51, v147
	v_add_f32_e32 v214, 1.0, v214
	v_add_f32_e32 v215, 1.0, v215
	v_add_f32_e32 v216, 1.0, v216
	v_add_f32_e32 v217, 1.0, v217
	v_add_f32_e32 v218, 1.0, v218
	v_add_f32_e32 v219, 1.0, v219
	v_add_f32_e32 v220, 1.0, v220
	v_add_f32_e32 v221, 1.0, v221
	v_rcp_f32_e32 v214, v214
	v_rcp_f32_e32 v215, v215
	v_rcp_f32_e32 v216, v216
	v_rcp_f32_e32 v217, v217
	v_rcp_f32_e32 v218, v218
	v_rcp_f32_e32 v219, v219
	v_rcp_f32_e32 v220, v220
	v_rcp_f32_e32 v221, v221
	v_mul_f32_e32 v162, v162, v214
	v_mul_f32_e32 v163, v163, v215
	v_mul_f32_e32 v164, v164, v216
	v_mul_f32_e32 v165, v165, v217
	v_mul_f32_e32 v166, v166, v218
	v_mul_f32_e32 v167, v167, v219
	v_mul_f32_e32 v168, v168, v220
	v_mul_f32_e32 v169, v169, v221
	v_mul_f32_e32 v206, v206, v162
	v_mul_f32_e32 v207, v207, v163
	v_mul_f32_e32 v208, v208, v164
	v_mul_f32_e32 v209, v209, v165
	v_mul_f32_e32 v210, v210, v166
	v_mul_f32_e32 v211, v211, v167
	v_mul_f32_e32 v212, v212, v168
	v_mul_f32_e32 v213, v213, v169
	v_cvt_pk_bf16_f32 v206, v206, s0
	v_cvt_pk_bf16_f32 v207, v207, s0
	v_cvt_pk_bf16_f32 v208, v208, s0
	v_cvt_pk_bf16_f32 v209, v209, s0
	v_cvt_pk_bf16_f32 v210, v210, s0
	v_cvt_pk_bf16_f32 v211, v211, s0
	v_cvt_pk_bf16_f32 v212, v212, s0
	v_cvt_pk_bf16_f32 v213, v213, s0
	ds_write_b16 v160, v206 offset:16384
	ds_write_b16 v160, v207 offset:16640
	ds_write_b16 v160, v208 offset:16896
	ds_write_b16 v160, v209 offset:17152
	ds_write_b16 v161, v210 offset:16384
	ds_write_b16 v161, v211 offset:16640
	ds_write_b16 v161, v212 offset:16896
	ds_write_b16 v161, v213 offset:17152
	v_mul_f32_e32 v162, v44, v148
	v_mul_f32_e32 v163, v45, v149
	v_mul_f32_e32 v164, v46, v150
	v_mul_f32_e32 v165, v47, v151
	v_mul_f32_e32 v166, v36, v148
	v_mul_f32_e32 v167, v37, v149
	v_mul_f32_e32 v168, v38, v150
	v_mul_f32_e32 v169, v39, v151
	v_mul_f32_e32 v214, 0xbfb8aa3b, v162
	v_mul_f32_e32 v215, 0xbfb8aa3b, v163
	v_mul_f32_e32 v216, 0xbfb8aa3b, v164
	v_mul_f32_e32 v217, 0xbfb8aa3b, v165
	v_mul_f32_e32 v218, 0xbfb8aa3b, v166
	v_mul_f32_e32 v219, 0xbfb8aa3b, v167
	v_mul_f32_e32 v220, 0xbfb8aa3b, v168
	v_mul_f32_e32 v221, 0xbfb8aa3b, v169
	v_exp_f32_e32 v214, v214
	v_exp_f32_e32 v215, v215
	v_exp_f32_e32 v216, v216
	v_exp_f32_e32 v217, v217
	v_exp_f32_e32 v218, v218
	v_exp_f32_e32 v219, v219
	v_exp_f32_e32 v220, v220
	v_exp_f32_e32 v221, v221
	v_mul_f32_e32 v206, v40, v148
	v_mul_f32_e32 v207, v41, v149
	v_mul_f32_e32 v208, v42, v150
	v_mul_f32_e32 v209, v43, v151
	v_mul_f32_e32 v210, v32, v148
	v_mul_f32_e32 v211, v33, v149
	v_mul_f32_e32 v212, v34, v150
	v_mul_f32_e32 v213, v35, v151
	v_add_f32_e32 v214, 1.0, v214
	v_add_f32_e32 v215, 1.0, v215
	v_add_f32_e32 v216, 1.0, v216
	v_add_f32_e32 v217, 1.0, v217
	v_add_f32_e32 v218, 1.0, v218
	v_add_f32_e32 v219, 1.0, v219
	v_add_f32_e32 v220, 1.0, v220
	v_add_f32_e32 v221, 1.0, v221
	v_rcp_f32_e32 v214, v214
	v_rcp_f32_e32 v215, v215
	v_rcp_f32_e32 v216, v216
	v_rcp_f32_e32 v217, v217
	v_rcp_f32_e32 v218, v218
	v_rcp_f32_e32 v219, v219
	v_rcp_f32_e32 v220, v220
	v_rcp_f32_e32 v221, v221
	v_mul_f32_e32 v162, v162, v214
	v_mul_f32_e32 v163, v163, v215
	v_mul_f32_e32 v164, v164, v216
	v_mul_f32_e32 v165, v165, v217
	v_mul_f32_e32 v166, v166, v218
	v_mul_f32_e32 v167, v167, v219
	v_mul_f32_e32 v168, v168, v220
	v_mul_f32_e32 v169, v169, v221
	v_mul_f32_e32 v206, v206, v162
	v_mul_f32_e32 v207, v207, v163
	v_mul_f32_e32 v208, v208, v164
	v_mul_f32_e32 v209, v209, v165
	v_mul_f32_e32 v210, v210, v166
	v_mul_f32_e32 v211, v211, v167
	v_mul_f32_e32 v212, v212, v168
	v_mul_f32_e32 v213, v213, v169
	v_cvt_pk_bf16_f32 v206, v206, s0
	v_cvt_pk_bf16_f32 v207, v207, s0
	v_cvt_pk_bf16_f32 v208, v208, s0
	v_cvt_pk_bf16_f32 v209, v209, s0
	v_cvt_pk_bf16_f32 v210, v210, s0
	v_cvt_pk_bf16_f32 v211, v211, s0
	v_cvt_pk_bf16_f32 v212, v212, s0
	v_cvt_pk_bf16_f32 v213, v213, s0
	ds_write_b16 v160, v206 offset:20480
	ds_write_b16 v160, v207 offset:20736
	ds_write_b16 v160, v208 offset:20992
	ds_write_b16 v160, v209 offset:21248
	ds_write_b16 v161, v210 offset:20480
	ds_write_b16 v161, v211 offset:20736
	ds_write_b16 v161, v212 offset:20992
	ds_write_b16 v161, v213 offset:21248
	v_mul_f32_e32 v162, v28, v152
	v_mul_f32_e32 v163, v29, v153
	v_mul_f32_e32 v164, v30, v154
	v_mul_f32_e32 v165, v31, v155
	v_mul_f32_e32 v166, v20, v152
	v_mul_f32_e32 v167, v21, v153
	v_mul_f32_e32 v168, v22, v154
	v_mul_f32_e32 v169, v23, v155
	v_mul_f32_e32 v214, 0xbfb8aa3b, v162
	v_mul_f32_e32 v215, 0xbfb8aa3b, v163
	v_mul_f32_e32 v216, 0xbfb8aa3b, v164
	v_mul_f32_e32 v217, 0xbfb8aa3b, v165
	v_mul_f32_e32 v218, 0xbfb8aa3b, v166
	v_mul_f32_e32 v219, 0xbfb8aa3b, v167
	v_mul_f32_e32 v220, 0xbfb8aa3b, v168
	v_mul_f32_e32 v221, 0xbfb8aa3b, v169
	v_exp_f32_e32 v214, v214
	v_exp_f32_e32 v215, v215
	v_exp_f32_e32 v216, v216
	v_exp_f32_e32 v217, v217
	v_exp_f32_e32 v218, v218
	v_exp_f32_e32 v219, v219
	v_exp_f32_e32 v220, v220
	v_exp_f32_e32 v221, v221
	v_mul_f32_e32 v206, v24, v152
; __device__ __forceinline__ float silu_(float x) { return x * rcp_(1.f + __expf(-x)); }
; template <int EPI>
; __device__ __forceinline__ void gemm_phase(const Params& p, const u16* __restrict__ A, const u16* __restrict__ Bt, int K, int nN,
;                            u16* __restrict__ Cout, int ldc) {
;     ...
;           u16* d = stg + (wr * 128 + m * 16 + fqe * 4 + j) * 128 + (fre & 7);
; #pragma unroll
;           for (int n2 = 0; n2 < 2; ++n2) {
;             const float g = acc[m][2 * n2][j] * rs, u = acc[m][2 * n2 + 1][j] * rs;
;             const int chunk = (wc * 4 + n2 * 2 + (fre >> 3)) ^ fqe;
;             d[chunk * 8] = f2bf(silu_(g) * u);
;           }
;         }
;         __builtin_amdgcn_sched_barrier(0);
;       }
;       __syncthreads();
; #pragma unroll
;       for (int it = 0; it < 8; ++it) {
;         const int id = it * 512 + tide, r = id >> 4, ck = id & 15;
;         const uint4 v = *(const uint4*)(stg + r * 128 + ((ck ^ ((r >> 2) & 3)) * 8));
;         { typedef __attribute__((ext_vector_type(4))) unsigned u32x4_; const u32x4_ t_ = {v.x, v.y, v.z, v.w};
;           __builtin_nontemporal_store(t_, (u32x4_*)(Cout + (unsigned)(brow + r) * (unsigned)ldc + (unsigned)((bcol >> 1) + ck * 8))); }
;       }
;       asm volatile("s_waitcnt lgkmcnt(0)" ::: "memory"); __builtin_amdgcn_s_barrier();
	v_mul_f32_e32 v207, v25, v153
	v_mul_f32_e32 v208, v26, v154
	v_mul_f32_e32 v209, v27, v155
	v_mul_f32_e32 v210, v16, v152
	v_mul_f32_e32 v211, v17, v153
	v_mul_f32_e32 v212, v18, v154
	v_mul_f32_e32 v213, v19, v155
	v_add_f32_e32 v214, 1.0, v214
	v_add_f32_e32 v215, 1.0, v215
	v_add_f32_e32 v216, 1.0, v216
	v_add_f32_e32 v217, 1.0, v217
	v_add_f32_e32 v218, 1.0, v218
	v_add_f32_e32 v219, 1.0, v219
	v_add_f32_e32 v220, 1.0, v220
	v_add_f32_e32 v221, 1.0, v221
	v_rcp_f32_e32 v214, v214
	v_rcp_f32_e32 v215, v215
	v_rcp_f32_e32 v216, v216
	v_rcp_f32_e32 v217, v217
	v_rcp_f32_e32 v218, v218
	v_rcp_f32_e32 v219, v219
	v_rcp_f32_e32 v220, v220
	v_rcp_f32_e32 v221, v221
	v_mul_f32_e32 v162, v162, v214
	v_mul_f32_e32 v163, v163, v215
	v_mul_f32_e32 v164, v164, v216
	v_mul_f32_e32 v165, v165, v217
	v_mul_f32_e32 v166, v166, v218
	v_mul_f32_e32 v167, v167, v219
	v_mul_f32_e32 v168, v168, v220
	v_mul_f32_e32 v169, v169, v221
	v_mul_f32_e32 v206, v206, v162
	v_mul_f32_e32 v207, v207, v163
	v_mul_f32_e32 v208, v208, v164
	v_mul_f32_e32 v209, v209, v165
	v_mul_f32_e32 v210, v210, v166
	v_mul_f32_e32 v211, v211, v167
	v_mul_f32_e32 v212, v212, v168
	v_mul_f32_e32 v213, v213, v169
	v_cvt_pk_bf16_f32 v206, v206, s0
	v_cvt_pk_bf16_f32 v207, v207, s0
	v_cvt_pk_bf16_f32 v208, v208, s0
	v_cvt_pk_bf16_f32 v209, v209, s0
	v_cvt_pk_bf16_f32 v210, v210, s0
	v_cvt_pk_bf16_f32 v211, v211, s0
	v_cvt_pk_bf16_f32 v212, v212, s0
	v_cvt_pk_bf16_f32 v213, v213, s0
	ds_write_b16 v160, v206 offset:24576
	ds_write_b16 v160, v207 offset:24832
	ds_write_b16 v160, v208 offset:25088
	ds_write_b16 v160, v209 offset:25344
	ds_write_b16 v161, v210 offset:24576
	ds_write_b16 v161, v211 offset:24832
	ds_write_b16 v161, v212 offset:25088
	ds_write_b16 v161, v213 offset:25344
	v_mul_f32_e32 v162, v12, v156
	v_mul_f32_e32 v163, v13, v157
	v_mul_f32_e32 v164, v14, v158
	v_mul_f32_e32 v165, v15, v159
	v_mul_f32_e32 v166, v4, v156
	v_mul_f32_e32 v167, v5, v157
	v_mul_f32_e32 v168, v6, v158
	v_mul_f32_e32 v169, v7, v159
	v_mul_f32_e32 v214, 0xbfb8aa3b, v162
	v_mul_f32_e32 v215, 0xbfb8aa3b, v163
	v_mul_f32_e32 v216, 0xbfb8aa3b, v164
	v_mul_f32_e32 v217, 0xbfb8aa3b, v165
	v_mul_f32_e32 v218, 0xbfb8aa3b, v166
	v_mul_f32_e32 v219, 0xbfb8aa3b, v167
	v_mul_f32_e32 v220, 0xbfb8aa3b, v168
	v_mul_f32_e32 v221, 0xbfb8aa3b, v169
	v_exp_f32_e32 v214, v214
	v_exp_f32_e32 v215, v215
	v_exp_f32_e32 v216, v216
	v_exp_f32_e32 v217, v217
	v_exp_f32_e32 v218, v218
	v_exp_f32_e32 v219, v219
	v_exp_f32_e32 v220, v220
	v_exp_f32_e32 v221, v221
	v_mul_f32_e32 v206, v8, v156
	v_mul_f32_e32 v207, v9, v157
	v_mul_f32_e32 v208, v10, v158
	v_mul_f32_e32 v209, v11, v159
	v_mul_f32_e32 v210, v0, v156
	v_mul_f32_e32 v211, v1, v157
	v_mul_f32_e32 v212, v2, v158
	v_mul_f32_e32 v213, v3, v159
	v_add_f32_e32 v214, 1.0, v214
	v_add_f32_e32 v215, 1.0, v215
	v_add_f32_e32 v216, 1.0, v216
	v_add_f32_e32 v217, 1.0, v217
	v_add_f32_e32 v218, 1.0, v218
	v_add_f32_e32 v219, 1.0, v219
	v_add_f32_e32 v220, 1.0, v220
	v_add_f32_e32 v221, 1.0, v221
	v_rcp_f32_e32 v214, v214
	v_rcp_f32_e32 v215, v215
	v_rcp_f32_e32 v216, v216
	v_rcp_f32_e32 v217, v217
	v_rcp_f32_e32 v218, v218
	v_rcp_f32_e32 v219, v219
	v_rcp_f32_e32 v220, v220
	v_rcp_f32_e32 v221, v221
	v_mul_f32_e32 v162, v162, v214
	v_mul_f32_e32 v163, v163, v215
	v_mul_f32_e32 v164, v164, v216
	v_mul_f32_e32 v165, v165, v217
	v_mul_f32_e32 v166, v166, v218
	v_mul_f32_e32 v167, v167, v219
	v_mul_f32_e32 v168, v168, v220
	v_mul_f32_e32 v169, v169, v221
	v_mul_f32_e32 v206, v206, v162
	v_mul_f32_e32 v207, v207, v163
	v_mul_f32_e32 v208, v208, v164
	v_mul_f32_e32 v209, v209, v165
	v_mul_f32_e32 v210, v210, v166
	v_mul_f32_e32 v211, v211, v167
	v_mul_f32_e32 v212, v212, v168
	v_mul_f32_e32 v213, v213, v169
	v_cvt_pk_bf16_f32 v206, v206, s0
	v_cvt_pk_bf16_f32 v207, v207, s0
	v_cvt_pk_bf16_f32 v208, v208, s0
	v_cvt_pk_bf16_f32 v209, v209, s0
	v_cvt_pk_bf16_f32 v210, v210, s0
	v_cvt_pk_bf16_f32 v211, v211, s0
	v_cvt_pk_bf16_f32 v212, v212, s0
	v_cvt_pk_bf16_f32 v213, v213, s0
	ds_write_b16 v160, v206 offset:28672
	ds_write_b16 v160, v207 offset:28928
	ds_write_b16 v160, v208 offset:29184
	ds_write_b16 v160, v209 offset:29440
	ds_write_b16 v161, v210 offset:28672
	ds_write_b16 v161, v211 offset:28928
	ds_write_b16 v161, v212 offset:29184
	ds_write_b16 v161, v213 offset:29440
	v_mov_b32_e32 v128, v173
	v_and_b32_e32 v0, 15, v128
	v_lshrrev_b32_e32 v1, 6, v128
	v_bitop3_b32 v1, v1, v0, 3 bitop3:0x6c
	s_lshl_b32 s2, s39, 7
	v_lshl_or_b32 v8, v1, 4, v188
	v_lshl_or_b32 v0, v0, 3, s2
	v_mov_b32_e32 v1, v172
	v_ashrrev_i32_e32 v6, 4, v128
	v_lshl_add_u64 v[4:5], v[0:1], 1, s[4:5]
	v_lshl_add_u32 v0, v6, 8, v8
	s_waitcnt lgkmcnt(0)
	s_barrier
	ds_read_b128 v[16:19], v0 offset:0
	ds_read_b128 v[20:23], v0 offset:8192
	ds_read_b128 v[24:27], v0 offset:16384
	ds_read_b128 v[28:31], v0 offset:24576
	ds_read_b128 v[32:35], v0 offset:32768
	ds_read_b128 v[36:39], v0 offset:40960
	ds_read_b128 v[40:43], v0 offset:49152
	ds_read_b128 v[44:47], v0 offset:57344
	v_add_u32_e32 v6, s12, v6
	v_mul_lo_u32 v6, v6, s58
	v_mov_b32_e32 v7, v172
	v_lshl_add_u64 v[48:49], v[6:7], 1, v[4:5]
	s_mov_b64 s[2:3], 0x2c000
	s_mov_b64 s[26:27], -1
	s_and_b64 vcc, exec, s[14:15]
	v_lshl_add_u64 v[50:51], v[48:49], 0, s[2:3]
	v_lshl_add_u64 v[52:53], v[50:51], 0, s[2:3]
	v_lshl_add_u64 v[54:55], v[52:53], 0, s[2:3]
	v_lshl_add_u64 v[56:57], v[54:55], 0, s[2:3]
	v_lshl_add_u64 v[58:59], v[56:57], 0, s[2:3]
	v_lshl_add_u64 v[60:61], v[58:59], 0, s[2:3]
	v_lshl_add_u64 v[62:63], v[60:61], 0, s[2:3]
	s_waitcnt lgkmcnt(7)
	global_store_dwordx4 v[48:49], v[16:19], off nt
	s_waitcnt lgkmcnt(6)
	global_store_dwordx4 v[50:51], v[20:23], off nt
	s_waitcnt lgkmcnt(5)
	global_store_dwordx4 v[52:53], v[24:27], off nt
	s_waitcnt lgkmcnt(4)
	global_store_dwordx4 v[54:55], v[28:31], off nt
	s_waitcnt lgkmcnt(3)
	global_store_dwordx4 v[56:57], v[32:35], off nt
	s_waitcnt lgkmcnt(2)
	global_store_dwordx4 v[58:59], v[36:39], off nt
	s_waitcnt lgkmcnt(1)
	global_store_dwordx4 v[60:61], v[40:43], off nt
	s_waitcnt lgkmcnt(0)
	global_store_dwordx4 v[62:63], v[44:47], off nt
	s_waitcnt lgkmcnt(0)
	s_barrier
	s_cbranch_vccnz .LBB0_1153
